# v43 + write-through (sc1) stores for the prologue's transposed bf16 weights
# baseline (speedup 1.0000x reference)
; __device__ __forceinline__ unsigned cvt_pk_bf16(float lo, float hi) { unsigned r; asm volatile("v_cvt_pk_bf16_f32 %0, %1, %2" : "=v"(r) : "v"(lo), "v"(hi)); return r; }
; #define LAS __attribute__((address_space(3)))
; #define TR_LOAD(t, item) do { const int nblk_ = N / 32, kb_ = (item) / nblk_, nb_ = (item) % nblk_; \
;     _Pragma("unroll") for (int i = 0; i < 8; ++i) (t)[i] = *(const f32x4*)(W + (size_t)(64 * kb_ + 8 * i + (lane >> 3)) * N + 32 * nb_ + 4 * (lane & 7)); } while (0)
; __device__ __forceinline__ void transpose_put(const f32x4 (&t)[8], int K, int N, bf16_t* WT, int mode, int row_off, LAS float* scr, int item, int lane) {
;     ...
;     const int c = lane & 7;
; #pragma unroll
;     for (int j = 0; j < 4; ++j) { const int n = (lane >> 3) + 8 * j; const LAS float* s = scr + (8 * c) * 33 + n;
;         u32x4 o; o.x = cvt_pk_bf16(s[0 * 33], s[1 * 33]); o.y = cvt_pk_bf16(s[2 * 33], s[3 * 33]); o.z = cvt_pk_bf16(s[4 * 33], s[5 * 33]); o.w = cvt_pk_bf16(s[6 * 33], s[7 * 33]);
;         *(u32x4*)(WT + (size_t)(r0 + n) * K + k0 + 8 * c) = o; }
; __device__ __forceinline__ void transpose_matrix(const float* W, int K, int N, bf16_t* WT, int mode, int row_off, LAS float* scr, int gw, int NGW, int lane) {
;     ...
;         const int it1 = it + NGW; if (it1 < nitems) TR_LOAD(tb, it1);
;         transpose_put(ta, K, N, WT, mode, row_off, scr, it, lane);
;         if (it1 >= nitems) break;
.LBB0_999:
	v_add_u32_e32 v3, s22, v5
	s_lshl_b32 s20, s23, 6
	v_mad_u64_u32 v[88:89], s[50:51], v3, s43, 0
	s_ashr_i32 s21, s20, 31
	v_ashrrev_i32_e32 v81, 31, v3
	v_mov_b32_e32 v92, v89
	ds_read2_b32 v[82:83], v79 offset1:33
	v_lshl_add_u64 v[90:91], s[20:21], 1, v[10:11]
	v_mad_u64_u32 v[92:93], s[20:21], v81, s43, v[92:93]
	s_waitcnt lgkmcnt(0)
	v_cvt_pk_bf16_f32 v82, v82, v83
	ds_read2_b32 v[84:85], v79 offset0:66 offset1:99
	v_mov_b32_e32 v89, v92
	s_waitcnt lgkmcnt(0)
	v_cvt_pk_bf16_f32 v83, v84, v85
	ds_read2_b32 v[84:85], v79 offset0:132 offset1:165
	v_lshl_add_u64 v[88:89], v[88:89], 1, v[90:91]
	v_add_u32_e32 v3, s22, v9
	s_waitcnt lgkmcnt(0)
	v_cvt_pk_bf16_f32 v84, v84, v85
	ds_read2_b32 v[86:87], v79 offset0:198 offset1:231
	s_waitcnt lgkmcnt(0)
	v_cvt_pk_bf16_f32 v85, v86, v87
	global_store_dwordx4 v[88:89], v[82:85], off sc1
	v_mad_u64_u32 v[88:89], s[20:21], v3, s43, 0
	v_ashrrev_i32_e32 v81, 31, v3
	v_mov_b32_e32 v92, v89
	v_mad_u64_u32 v[92:93], s[20:21], v81, s43, v[92:93]
	ds_read2_b32 v[86:87], v79 offset0:8 offset1:41
	s_waitcnt lgkmcnt(0)
	v_cvt_pk_bf16_f32 v82, v86, v87
	ds_read2_b32 v[84:85], v79 offset0:74 offset1:107
	v_mov_b32_e32 v89, v92
	s_waitcnt lgkmcnt(0)
	v_cvt_pk_bf16_f32 v83, v84, v85
	ds_read2_b32 v[84:85], v79 offset0:140 offset1:173
	v_lshl_add_u64 v[88:89], v[88:89], 1, v[90:91]
	v_add_u32_e32 v3, s22, v13
	s_waitcnt lgkmcnt(0)
	v_cvt_pk_bf16_f32 v84, v84, v85
	ds_read2_b32 v[86:87], v79 offset0:206 offset1:239
	s_waitcnt lgkmcnt(0)
	v_cvt_pk_bf16_f32 v85, v86, v87
	global_store_dwordx4 v[88:89], v[82:85], off sc1
	v_mad_u64_u32 v[88:89], s[20:21], v3, s43, 0
	ds_read2_b32 v[86:87], v79 offset0:16 offset1:49
	s_waitcnt lgkmcnt(0)
	v_cvt_pk_bf16_f32 v82, v86, v87
	ds_read2_b32 v[84:85], v79 offset0:82 offset1:115
	v_ashrrev_i32_e32 v81, 31, v3
	v_mov_b32_e32 v92, v89
	s_waitcnt lgkmcnt(0)
	v_cvt_pk_bf16_f32 v83, v84, v85
	ds_read2_b32 v[84:85], v79 offset0:148 offset1:181
	v_mad_u64_u32 v[92:93], s[20:21], v81, s43, v[92:93]
	s_waitcnt lgkmcnt(0)
	v_cvt_pk_bf16_f32 v84, v84, v85
	ds_read2_b32 v[86:87], v79 offset0:214 offset1:247
	v_mov_b32_e32 v89, v92
	s_waitcnt lgkmcnt(0)
	v_cvt_pk_bf16_f32 v85, v86, v87
	ds_read2_b32 v[86:87], v79 offset0:24 offset1:57
	v_lshl_add_u64 v[88:89], v[88:89], 1, v[90:91]
	v_add_u32_e32 v3, s22, v78
	global_store_dwordx4 v[88:89], v[82:85], off sc1
	v_ashrrev_i32_e32 v81, 31, v3
	s_add_i32 s49, s48, s88
	s_waitcnt lgkmcnt(0)
	v_cvt_pk_bf16_f32 v82, v86, v87
	v_mad_u64_u32 v[86:87], s[20:21], v3, s43, 0
	v_mov_b32_e32 v92, v87
	v_mad_u64_u32 v[92:93], s[20:21], v81, s43, v[92:93]
	ds_read2_b32 v[84:85], v79 offset0:90 offset1:123
	v_mov_b32_e32 v87, v92
	s_waitcnt lgkmcnt(0)
	v_cvt_pk_bf16_f32 v83, v84, v85
	ds_read2_b32 v[84:85], v79 offset0:156 offset1:189
	v_lshl_add_u64 v[86:87], v[86:87], 1, v[90:91]
	s_waitcnt lgkmcnt(0)
	v_cvt_pk_bf16_f32 v84, v84, v85
	ds_read2_b32 v[88:89], v79 offset0:222 offset1:255
	s_waitcnt lgkmcnt(0)
	v_cvt_pk_bf16_f32 v85, v88, v89
	global_store_dwordx4 v[86:87], v[82:85], off sc1
	s_waitcnt lgkmcnt(0)
	s_cmp_ge_i32 s49, s25
	s_cselect_b64 s[20:21], -1, 0

; __device__ __forceinline__ unsigned cvt_pk_bf16(float lo, float hi) { unsigned r; asm volatile("v_cvt_pk_bf16_f32 %0, %1, %2" : "=v"(r) : "v"(lo), "v"(hi)); return r; }
; #define LAS __attribute__((address_space(3)))
; __device__ __forceinline__ void transpose_put(const f32x4 (&t)[8], int K, int N, bf16_t* WT, int mode, int row_off, LAS float* scr, int item, int lane) {
;     ...
;     for (int j = 0; j < 4; ++j) { const int n = (lane >> 3) + 8 * j; const LAS float* s = scr + (8 * c) * 33 + n;
;         u32x4 o; o.x = cvt_pk_bf16(s[0 * 33], s[1 * 33]); o.y = cvt_pk_bf16(s[2 * 33], s[3 * 33]); o.z = cvt_pk_bf16(s[4 * 33], s[5 * 33]); o.w = cvt_pk_bf16(s[6 * 33], s[7 * 33]);
;         *(u32x4*)(WT + (size_t)(r0 + n) * K + k0 + 8 * c) = o; }
.LBB0_1007:
	v_add_u32_e32 v100, s50, v5
	s_lshl_b32 s22, s51, 6
	v_ashrrev_i32_e32 v105, 31, v100
	v_mad_u64_u32 v[100:101], s[52:53], v100, s43, 0
	s_ashr_i32 s23, s22, 31
	v_mov_b32_e32 v104, v101
	ds_read2_b32 v[94:95], v79 offset1:33
	v_lshl_add_u64 v[102:103], s[22:23], 1, v[10:11]
	v_mad_u64_u32 v[104:105], s[22:23], v105, s43, v[104:105]
	s_waitcnt lgkmcnt(0)
	v_cvt_pk_bf16_f32 v94, v94, v95
	ds_read2_b32 v[96:97], v79 offset0:66 offset1:99
	v_mov_b32_e32 v101, v104
	s_waitcnt lgkmcnt(0)
	v_cvt_pk_bf16_f32 v95, v96, v97
	ds_read2_b32 v[96:97], v79 offset0:132 offset1:165
	v_lshl_add_u64 v[100:101], v[100:101], 1, v[102:103]
	s_waitcnt lgkmcnt(0)
	v_cvt_pk_bf16_f32 v96, v96, v97
	ds_read2_b32 v[98:99], v79 offset0:198 offset1:231
	s_waitcnt lgkmcnt(0)
	v_cvt_pk_bf16_f32 v97, v98, v99
	global_store_dwordx4 v[100:101], v[94:97], off sc1
	v_add_u32_e32 v100, s50, v9
	v_ashrrev_i32_e32 v105, 31, v100
	v_mad_u64_u32 v[100:101], s[22:23], v100, s43, 0
	v_mov_b32_e32 v104, v101
	v_mad_u64_u32 v[104:105], s[22:23], v105, s43, v[104:105]
	ds_read2_b32 v[98:99], v79 offset0:8 offset1:41
	s_waitcnt lgkmcnt(0)
	v_cvt_pk_bf16_f32 v94, v98, v99
	ds_read2_b32 v[96:97], v79 offset0:74 offset1:107
	v_mov_b32_e32 v101, v104
	s_waitcnt lgkmcnt(0)
	v_cvt_pk_bf16_f32 v95, v96, v97
	ds_read2_b32 v[96:97], v79 offset0:140 offset1:173
	v_lshl_add_u64 v[100:101], v[100:101], 1, v[102:103]
	s_waitcnt lgkmcnt(0)
	v_cvt_pk_bf16_f32 v96, v96, v97
	ds_read2_b32 v[98:99], v79 offset0:206 offset1:239
	s_waitcnt lgkmcnt(0)
	v_cvt_pk_bf16_f32 v97, v98, v99
	global_store_dwordx4 v[100:101], v[94:97], off sc1
	v_add_u32_e32 v100, s50, v13
	v_ashrrev_i32_e32 v105, 31, v100
	v_mad_u64_u32 v[100:101], s[22:23], v100, s43, 0
	ds_read2_b32 v[98:99], v79 offset0:16 offset1:49
	s_waitcnt lgkmcnt(0)
	v_cvt_pk_bf16_f32 v94, v98, v99
	ds_read2_b32 v[96:97], v79 offset0:82 offset1:115
	v_mov_b32_e32 v104, v101
	s_waitcnt lgkmcnt(0)
	v_cvt_pk_bf16_f32 v95, v96, v97
	ds_read2_b32 v[96:97], v79 offset0:148 offset1:181
	v_mad_u64_u32 v[104:105], s[22:23], v105, s43, v[104:105]
	s_waitcnt lgkmcnt(0)
	v_cvt_pk_bf16_f32 v96, v96, v97
	ds_read2_b32 v[98:99], v79 offset0:214 offset1:247
	v_mov_b32_e32 v101, v104
	s_waitcnt lgkmcnt(0)
	v_cvt_pk_bf16_f32 v97, v98, v99
	ds_read2_b32 v[98:99], v79 offset0:24 offset1:57
	v_lshl_add_u64 v[100:101], v[100:101], 1, v[102:103]
	global_store_dwordx4 v[100:101], v[94:97], off sc1
	s_andn2_b64 vcc, exec, s[20:21]
	s_mov_b64 s[20:21], -1
	s_waitcnt lgkmcnt(0)
	v_cvt_pk_bf16_f32 v94, v98, v99
	v_add_u32_e32 v98, s50, v78
	v_ashrrev_i32_e32 v101, 31, v98
	v_mad_u64_u32 v[98:99], s[22:23], v98, s43, 0
	v_mov_b32_e32 v100, v99
	v_mad_u64_u32 v[100:101], s[22:23], v101, s43, v[100:101]
	ds_read2_b32 v[96:97], v79 offset0:90 offset1:123
	v_mov_b32_e32 v99, v100
	s_waitcnt lgkmcnt(0)
	v_cvt_pk_bf16_f32 v95, v96, v97
	ds_read2_b32 v[96:97], v79 offset0:156 offset1:189
	v_lshl_add_u64 v[98:99], v[98:99], 1, v[102:103]
	s_waitcnt lgkmcnt(0)
	v_cvt_pk_bf16_f32 v96, v96, v97
	ds_read2_b32 v[104:105], v79 offset0:222 offset1:255
	s_waitcnt lgkmcnt(0)
	v_cvt_pk_bf16_f32 v97, v104, v105
	global_store_dwordx4 v[98:99], v[94:97], off sc1
	s_waitcnt lgkmcnt(0)
	s_cbranch_vccnz .LBB0_1000
	s_add_i32 s20, s92, s49
	s_cmp_ge_i32 s20, s25
	s_cbranch_scc1 .LBB0_1010
	s_abs_i32 s22, s20
	s_mul_hi_u32 s23, s22, s46
	s_mul_i32 s49, s23, s24
	s_sub_i32 s22, s22, s49
	s_ashr_i32 s21, s20, 31
	s_add_i32 s49, s23, 1
	s_sub_i32 s50, s22, s24
	s_cmp_ge_u32 s22, s24
	s_cselect_b32 s23, s49, s23
	s_cselect_b32 s22, s50, s22
	s_add_i32 s49, s23, 1
	s_cmp_ge_u32 s22, s24
	s_cselect_b32 s22, s49, s23
	s_xor_b32 s22, s22, s21
	s_sub_i32 s21, s22, s21
	s_mul_i32 s22, s21, s24
	s_sub_i32 s20, s20, s22
	s_lshl_b32 s20, s20, 5
	s_lshl_b32 s22, s21, 6
	s_ashr_i32 s21, s20, 31
	v_or_b32_e32 v42, s22, v5
	v_lshl_add_u64 v[38:39], s[20:21], 2, v[6:7]
	s_ashr_i32 s20, s22, 31
	s_mul_i32 s22, s20, s44
	v_mad_u64_u32 v[14:15], s[20:21], v42, s44, 0
	v_or_b32_e32 v16, 8, v42
	v_or_b32_e32 v22, 16, v42
	v_or_b32_e32 v24, 24, v42
	v_or_b32_e32 v30, 32, v42
	v_or_b32_e32 v32, 40, v42
	v_or_b32_e32 v40, 48, v42
	v_or_b32_e32 v42, 56, v42
	v_mad_u64_u32 v[16:17], s[20:21], v16, s44, 0
	v_mad_u64_u32 v[22:23], s[20:21], v22, s44, 0
	v_mad_u64_u32 v[24:25], s[20:21], v24, s44, 0
	v_mad_u64_u32 v[30:31], s[20:21], v30, s44, 0
	v_mad_u64_u32 v[32:33], s[20:21], v32, s44, 0
	v_mad_u64_u32 v[40:41], s[20:21], v40, s44, 0
	v_mad_u64_u32 v[42:43], s[20:21], v42, s44, 0
	v_add_u32_e32 v15, s22, v15
	v_add_u32_e32 v17, s22, v17
	v_add_u32_e32 v23, s22, v23
	v_add_u32_e32 v25, s22, v25
	v_add_u32_e32 v31, s22, v31
	v_add_u32_e32 v33, s22, v33
	v_add_u32_e32 v41, s22, v41
	v_add_u32_e32 v43, s22, v43
	v_lshl_add_u64 v[14:15], v[14:15], 2, v[38:39]
	v_lshl_add_u64 v[18:19], v[16:17], 2, v[38:39]
	v_lshl_add_u64 v[22:23], v[22:23], 2, v[38:39]
	v_lshl_add_u64 v[26:27], v[24:25], 2, v[38:39]
	v_lshl_add_u64 v[30:31], v[30:31], 2, v[38:39]
	v_lshl_add_u64 v[34:35], v[32:33], 2, v[38:39]
	v_lshl_add_u64 v[40:41], v[40:41], 2, v[38:39]
	v_lshl_add_u64 v[42:43], v[42:43], 2, v[38:39]
	global_load_dwordx4 v[14:17], v[14:15], off
	s_nop 0
	global_load_dwordx4 v[18:21], v[18:19], off
	s_nop 0
	global_load_dwordx4 v[22:25], v[22:23], off
	s_nop 0
	global_load_dwordx4 v[26:29], v[26:27], off
	s_nop 0
	global_load_dwordx4 v[30:33], v[30:31], off
	s_nop 0
	global_load_dwordx4 v[34:37], v[34:35], off
	s_nop 0
	global_load_dwordx4 v[38:41], v[40:41], off
	s_nop 0
	global_load_dwordx4 v[42:45], v[42:43], off
